# v16 + NSA selected-branch V^T buffer re-laid out in contiguous 1-KiB MFMA-operand tiles (producer epilogue stores + stage C loads): 8 cache lines per load instruction instead of 16
# speedup vs baseline: 1.0307x; 1.0307x over previous
; DI bf16_t f2bf(float a) { return (bf16_t)(pk2(a, 0.f) & 0xffffu); }
;   DI void store(int m, int n, float a, float b, float c, float d) const {
;     int bb = m >> 13, s = m & (SEQ - 1);
;     if (n >= C_VS && n < C_KW) { int e = n - C_VS; bf16_t* p = vsT + ((size_t)(bb * 128 + e)) * SEQ + s; p[0] = f2bf(a); p[SEQ] = f2bf(b); p[2 * SEQ] = f2bf(c); p[3 * SEQ] = f2bf(d); }
.LBB0_277:
	s_andn2_saveexec_b64 s[18:19], s[18:19]
	s_cbranch_execz .LBB0_279
	v_lshrrev_b32_e32 v160, 14, v148
	v_and_b32_e32 v180, 0x1c0, v160
	v_lshlrev_b32_e32 v180, 14, v180
	v_bfe_u32 v161, v160, 4, 2
	v_lshl_or_b32 v180, v161, 11, v180
	v_and_b32_e32 v161, 15, v160
	v_lshl_or_b32 v180, v161, 6, v180
	v_lshrrev_b32_e32 v161, 6, v158
	v_lshl_or_b32 v180, v161, 13, v180
	v_bfe_u32 v161, v158, 5, 1
	v_lshl_or_b32 v180, v161, 10, v180
	v_and_b32_e32 v161, 31, v158
	v_lshl_or_b32 v180, v161, 1, v180
	v_mov_b32_e32 v181, v1
	v_lshl_add_u64 v[160:161], s[10:11], 0, v[180:181]
	v_cvt_pk_bf16_f32 v126, v126, s0
	flat_store_short v[160:161], v126
	v_add_co_u32_e32 v126, vcc, 0x40, v160
	v_cvt_pk_bf16_f32 v159, v127, s0
	s_nop 0
	v_addc_co_u32_e32 v127, vcc, 0, v161, vcc
	flat_store_short v[126:127], v159
	v_add_co_u32_e32 v126, vcc, 0x80, v160
	v_cvt_pk_bf16_f32 v128, v128, s0
	s_nop 0
	v_addc_co_u32_e32 v127, vcc, 0, v161, vcc
	flat_store_short v[126:127], v128
	v_add_co_u32_e32 v126, vcc, 0xc0, v160
	v_cvt_pk_bf16_f32 v128, v129, s0
	s_nop 0
	v_addc_co_u32_e32 v127, vcc, 0, v161, vcc
	flat_store_short v[126:127], v128

; DI bf16_t f2bf(float a) { return (bf16_t)(pk2(a, 0.f) & 0xffffu); }
;   DI void store(int m, int n, float a, float b, float c, float d) const {
;     int bb = m >> 13, s = m & (SEQ - 1);
;     if (n >= C_VS && n < C_KW) { int e = n - C_VS; bf16_t* p = vsT + ((size_t)(bb * 128 + e)) * SEQ + s; p[0] = f2bf(a); p[SEQ] = f2bf(b); p[2 * SEQ] = f2bf(c); p[3 * SEQ] = f2bf(d); }
.LBB0_285:
	s_andn2_saveexec_b64 s[6:7], s[6:7]
	s_cbranch_execz .LBB0_287
	v_lshrrev_b32_e32 v126, 14, v132
	v_and_b32_e32 v128, 0x1c0, v126
	v_lshlrev_b32_e32 v128, 14, v128
	v_bfe_u32 v127, v126, 4, 2
	v_lshl_or_b32 v128, v127, 11, v128
	v_and_b32_e32 v127, 15, v126
	v_lshl_or_b32 v128, v127, 6, v128
	v_lshrrev_b32_e32 v127, 6, v158
	v_lshl_or_b32 v128, v127, 13, v128
	v_bfe_u32 v127, v158, 5, 1
	v_lshl_or_b32 v128, v127, 10, v128
	v_and_b32_e32 v127, 31, v158
	v_lshl_or_b32 v128, v127, 1, v128
	v_mov_b32_e32 v129, v1
	v_lshl_add_u64 v[126:127], s[10:11], 0, v[128:129]
	v_cvt_pk_bf16_f32 v122, v122, s0
	flat_store_short v[126:127], v122
	v_add_co_u32_e32 v122, vcc, 0x40, v126
	v_cvt_pk_bf16_f32 v128, v123, s0
	s_nop 0
	v_addc_co_u32_e32 v123, vcc, 0, v127, vcc
	flat_store_short v[122:123], v128
	v_add_co_u32_e32 v122, vcc, 0x80, v126
	v_cvt_pk_bf16_f32 v124, v124, s0
	s_nop 0
	v_addc_co_u32_e32 v123, vcc, 0, v127, vcc
	flat_store_short v[122:123], v124
	v_add_co_u32_e32 v122, vcc, 0xc0, v126
	v_cvt_pk_bf16_f32 v124, v125, s0
	s_nop 0
	v_addc_co_u32_e32 v123, vcc, 0, v127, vcc
	flat_store_short v[122:123], v124

; DI bf16_t f2bf(float a) { return (bf16_t)(pk2(a, 0.f) & 0xffffu); }
;   DI void store(int m, int n, float a, float b, float c, float d) const {
;     int bb = m >> 13, s = m & (SEQ - 1);
;     if (n >= C_VS && n < C_KW) { int e = n - C_VS; bf16_t* p = vsT + ((size_t)(bb * 128 + e)) * SEQ + s; p[0] = f2bf(a); p[SEQ] = f2bf(b); p[2 * SEQ] = f2bf(c); p[3 * SEQ] = f2bf(d); }
.LBB0_300:
	s_andn2_saveexec_b64 s[18:19], s[18:19]
	s_cbranch_execz .LBB0_302
	v_lshrrev_b32_e32 v124, 14, v148
	v_and_b32_e32 v126, 0x1c0, v124
	v_lshlrev_b32_e32 v126, 14, v126
	v_bfe_u32 v125, v124, 4, 2
	v_lshl_or_b32 v126, v125, 11, v126
	v_and_b32_e32 v125, 15, v124
	v_lshl_or_b32 v126, v125, 6, v126
	v_lshrrev_b32_e32 v125, 6, v123
	v_lshl_or_b32 v126, v125, 13, v126
	v_bfe_u32 v125, v123, 5, 1
	v_lshl_or_b32 v126, v125, 10, v126
	v_and_b32_e32 v125, 31, v123
	v_lshl_or_b32 v126, v125, 1, v126
	v_mov_b32_e32 v127, v1
	v_lshl_add_u64 v[124:125], s[10:11], 0, v[126:127]
	v_cvt_pk_bf16_f32 v118, v118, s0
	flat_store_short v[124:125], v118
	v_add_co_u32_e32 v118, vcc, 0x40, v124
	v_cvt_pk_bf16_f32 v126, v119, s0
	s_nop 0
	v_addc_co_u32_e32 v119, vcc, 0, v125, vcc
	flat_store_short v[118:119], v126
	v_add_co_u32_e32 v118, vcc, 0x80, v124
	v_cvt_pk_bf16_f32 v120, v120, s0
	s_nop 0
	v_addc_co_u32_e32 v119, vcc, 0, v125, vcc
	flat_store_short v[118:119], v120
	v_add_co_u32_e32 v118, vcc, 0xc0, v124
	v_cvt_pk_bf16_f32 v120, v121, s0
	s_nop 0
	v_addc_co_u32_e32 v119, vcc, 0, v125, vcc
	flat_store_short v[118:119], v120

; DI bf16_t f2bf(float a) { return (bf16_t)(pk2(a, 0.f) & 0xffffu); }
;   DI void store(int m, int n, float a, float b, float c, float d) const {
;     int bb = m >> 13, s = m & (SEQ - 1);
;     if (n >= C_VS && n < C_KW) { int e = n - C_VS; bf16_t* p = vsT + ((size_t)(bb * 128 + e)) * SEQ + s; p[0] = f2bf(a); p[SEQ] = f2bf(b); p[2 * SEQ] = f2bf(c); p[3 * SEQ] = f2bf(d); }
.LBB0_308:
	s_andn2_saveexec_b64 s[6:7], s[6:7]
	s_cbranch_execz .LBB0_310
	v_lshrrev_b32_e32 v118, 14, v132
	v_and_b32_e32 v120, 0x1c0, v118
	v_lshlrev_b32_e32 v120, 14, v120
	v_bfe_u32 v119, v118, 4, 2
	v_lshl_or_b32 v120, v119, 11, v120
	v_and_b32_e32 v119, 15, v118
	v_lshl_or_b32 v120, v119, 6, v120
	v_lshrrev_b32_e32 v119, 6, v123
	v_lshl_or_b32 v120, v119, 13, v120
	v_bfe_u32 v119, v123, 5, 1
	v_lshl_or_b32 v120, v119, 10, v120
	v_and_b32_e32 v119, 31, v123
	v_lshl_or_b32 v120, v119, 1, v120
	v_mov_b32_e32 v121, v1
	v_lshl_add_u64 v[118:119], s[10:11], 0, v[120:121]
	v_cvt_pk_bf16_f32 v114, v114, s0
	flat_store_short v[118:119], v114
	v_add_co_u32_e32 v114, vcc, 0x40, v118
	v_cvt_pk_bf16_f32 v120, v115, s0
	s_nop 0
	v_addc_co_u32_e32 v115, vcc, 0, v119, vcc
	flat_store_short v[114:115], v120
	v_add_co_u32_e32 v114, vcc, 0x80, v118
	v_cvt_pk_bf16_f32 v116, v116, s0
	s_nop 0
	v_addc_co_u32_e32 v115, vcc, 0, v119, vcc
	flat_store_short v[114:115], v116
	v_add_co_u32_e32 v114, vcc, 0xc0, v118
	v_cvt_pk_bf16_f32 v116, v117, s0
	s_nop 0
	v_addc_co_u32_e32 v115, vcc, 0, v119, vcc
	flat_store_short v[114:115], v116

; DI bf16_t f2bf(float a) { return (bf16_t)(pk2(a, 0.f) & 0xffffu); }
;   DI void store(int m, int n, float a, float b, float c, float d) const {
;     int bb = m >> 13, s = m & (SEQ - 1);
;     if (n >= C_VS && n < C_KW) { int e = n - C_VS; bf16_t* p = vsT + ((size_t)(bb * 128 + e)) * SEQ + s; p[0] = f2bf(a); p[SEQ] = f2bf(b); p[2 * SEQ] = f2bf(c); p[3 * SEQ] = f2bf(d); }
.LBB0_323:
	s_andn2_saveexec_b64 s[18:19], s[18:19]
	s_cbranch_execz .LBB0_325
	v_lshrrev_b32_e32 v116, 14, v148
	v_and_b32_e32 v118, 0x1c0, v116
	v_lshlrev_b32_e32 v118, 14, v118
	v_bfe_u32 v117, v116, 4, 2
	v_lshl_or_b32 v118, v117, 11, v118
	v_and_b32_e32 v117, 15, v116
	v_lshl_or_b32 v118, v117, 6, v118
	v_lshrrev_b32_e32 v117, 6, v115
	v_lshl_or_b32 v118, v117, 13, v118
	v_bfe_u32 v117, v115, 5, 1
	v_lshl_or_b32 v118, v117, 10, v118
	v_and_b32_e32 v117, 31, v115
	v_lshl_or_b32 v118, v117, 1, v118
	v_mov_b32_e32 v119, v1
	v_lshl_add_u64 v[116:117], s[10:11], 0, v[118:119]
	v_cvt_pk_bf16_f32 v110, v110, s0
	flat_store_short v[116:117], v110
	v_add_co_u32_e32 v110, vcc, 0x40, v116
	v_cvt_pk_bf16_f32 v118, v111, s0
	s_nop 0
	v_addc_co_u32_e32 v111, vcc, 0, v117, vcc
	flat_store_short v[110:111], v118
	v_add_co_u32_e32 v110, vcc, 0x80, v116
	v_cvt_pk_bf16_f32 v112, v112, s0
	s_nop 0
	v_addc_co_u32_e32 v111, vcc, 0, v117, vcc
	flat_store_short v[110:111], v112
	v_add_co_u32_e32 v110, vcc, 0xc0, v116
	v_cvt_pk_bf16_f32 v112, v113, s0
	s_nop 0
	v_addc_co_u32_e32 v111, vcc, 0, v117, vcc
	flat_store_short v[110:111], v112

; DI bf16_t f2bf(float a) { return (bf16_t)(pk2(a, 0.f) & 0xffffu); }
;   DI void store(int m, int n, float a, float b, float c, float d) const {
;     int bb = m >> 13, s = m & (SEQ - 1);
;     if (n >= C_VS && n < C_KW) { int e = n - C_VS; bf16_t* p = vsT + ((size_t)(bb * 128 + e)) * SEQ + s; p[0] = f2bf(a); p[SEQ] = f2bf(b); p[2 * SEQ] = f2bf(c); p[3 * SEQ] = f2bf(d); }
.LBB0_331:
	s_andn2_saveexec_b64 s[6:7], s[6:7]
	s_cbranch_execz .LBB0_333
	v_lshrrev_b32_e32 v110, 14, v132
	v_and_b32_e32 v112, 0x1c0, v110
	v_lshlrev_b32_e32 v112, 14, v112
	v_bfe_u32 v111, v110, 4, 2
	v_lshl_or_b32 v112, v111, 11, v112
	v_and_b32_e32 v111, 15, v110
	v_lshl_or_b32 v112, v111, 6, v112
	v_lshrrev_b32_e32 v111, 6, v115
	v_lshl_or_b32 v112, v111, 13, v112
	v_bfe_u32 v111, v115, 5, 1
	v_lshl_or_b32 v112, v111, 10, v112
	v_and_b32_e32 v111, 31, v115
	v_lshl_or_b32 v112, v111, 1, v112
	v_mov_b32_e32 v113, v1
	v_lshl_add_u64 v[110:111], s[10:11], 0, v[112:113]
	v_cvt_pk_bf16_f32 v106, v106, s0
	flat_store_short v[110:111], v106
	v_add_co_u32_e32 v106, vcc, 0x40, v110
	v_cvt_pk_bf16_f32 v112, v107, s0
	s_nop 0
	v_addc_co_u32_e32 v107, vcc, 0, v111, vcc
	flat_store_short v[106:107], v112
	v_add_co_u32_e32 v106, vcc, 0x80, v110
	v_cvt_pk_bf16_f32 v108, v108, s0
	s_nop 0
	v_addc_co_u32_e32 v107, vcc, 0, v111, vcc
	flat_store_short v[106:107], v108
	v_add_co_u32_e32 v106, vcc, 0xc0, v110
	v_cvt_pk_bf16_f32 v108, v109, s0
	s_nop 0
	v_addc_co_u32_e32 v107, vcc, 0, v111, vcc
	flat_store_short v[106:107], v108

; DI bf16_t f2bf(float a) { return (bf16_t)(pk2(a, 0.f) & 0xffffu); }
;   DI void store(int m, int n, float a, float b, float c, float d) const {
;     int bb = m >> 13, s = m & (SEQ - 1);
;     if (n >= C_VS && n < C_KW) { int e = n - C_VS; bf16_t* p = vsT + ((size_t)(bb * 128 + e)) * SEQ + s; p[0] = f2bf(a); p[SEQ] = f2bf(b); p[2 * SEQ] = f2bf(c); p[3 * SEQ] = f2bf(d); }
.LBB0_346:
	s_andn2_saveexec_b64 s[18:19], s[18:19]
	s_cbranch_execz .LBB0_348
	v_lshrrev_b32_e32 v108, 14, v148
	v_and_b32_e32 v110, 0x1c0, v108
	v_lshlrev_b32_e32 v110, 14, v110
	v_bfe_u32 v109, v108, 4, 2
	v_lshl_or_b32 v110, v109, 11, v110
	v_and_b32_e32 v109, 15, v108
	v_lshl_or_b32 v110, v109, 6, v110
	v_lshrrev_b32_e32 v109, 6, v107
	v_lshl_or_b32 v110, v109, 13, v110
	v_bfe_u32 v109, v107, 5, 1
	v_lshl_or_b32 v110, v109, 10, v110
	v_and_b32_e32 v109, 31, v107
	v_lshl_or_b32 v110, v109, 1, v110
	v_mov_b32_e32 v111, v1
	v_lshl_add_u64 v[108:109], s[10:11], 0, v[110:111]
	v_cvt_pk_bf16_f32 v102, v102, s0
	flat_store_short v[108:109], v102
	v_add_co_u32_e32 v102, vcc, 0x40, v108
	v_cvt_pk_bf16_f32 v110, v103, s0
	s_nop 0
	v_addc_co_u32_e32 v103, vcc, 0, v109, vcc
	flat_store_short v[102:103], v110
	v_add_co_u32_e32 v102, vcc, 0x80, v108
	v_cvt_pk_bf16_f32 v104, v104, s0
	s_nop 0
	v_addc_co_u32_e32 v103, vcc, 0, v109, vcc
	flat_store_short v[102:103], v104
	v_add_co_u32_e32 v102, vcc, 0xc0, v108
	v_cvt_pk_bf16_f32 v104, v105, s0
	s_nop 0
	v_addc_co_u32_e32 v103, vcc, 0, v109, vcc
	flat_store_short v[102:103], v104

; DI bf16_t f2bf(float a) { return (bf16_t)(pk2(a, 0.f) & 0xffffu); }
;   DI void store(int m, int n, float a, float b, float c, float d) const {
;     int bb = m >> 13, s = m & (SEQ - 1);
;     if (n >= C_VS && n < C_KW) { int e = n - C_VS; bf16_t* p = vsT + ((size_t)(bb * 128 + e)) * SEQ + s; p[0] = f2bf(a); p[SEQ] = f2bf(b); p[2 * SEQ] = f2bf(c); p[3 * SEQ] = f2bf(d); }
.LBB0_354:
	s_andn2_saveexec_b64 s[6:7], s[6:7]
	s_cbranch_execz .LBB0_356
	v_lshrrev_b32_e32 v102, 14, v132
	v_and_b32_e32 v104, 0x1c0, v102
	v_lshlrev_b32_e32 v104, 14, v104
	v_bfe_u32 v103, v102, 4, 2
	v_lshl_or_b32 v104, v103, 11, v104
	v_and_b32_e32 v103, 15, v102
	v_lshl_or_b32 v104, v103, 6, v104
	v_lshrrev_b32_e32 v103, 6, v107
	v_lshl_or_b32 v104, v103, 13, v104
	v_bfe_u32 v103, v107, 5, 1
	v_lshl_or_b32 v104, v103, 10, v104
	v_and_b32_e32 v103, 31, v107
	v_lshl_or_b32 v104, v103, 1, v104
	v_mov_b32_e32 v105, v1
	v_lshl_add_u64 v[102:103], s[10:11], 0, v[104:105]
	v_cvt_pk_bf16_f32 v98, v98, s0
	flat_store_short v[102:103], v98
	v_add_co_u32_e32 v98, vcc, 0x40, v102
	v_cvt_pk_bf16_f32 v104, v99, s0
	s_nop 0
	v_addc_co_u32_e32 v99, vcc, 0, v103, vcc
	flat_store_short v[98:99], v104
	v_add_co_u32_e32 v98, vcc, 0x80, v102
	v_cvt_pk_bf16_f32 v100, v100, s0
	s_nop 0
	v_addc_co_u32_e32 v99, vcc, 0, v103, vcc
	flat_store_short v[98:99], v100
	v_add_co_u32_e32 v98, vcc, 0xc0, v102
	v_cvt_pk_bf16_f32 v100, v101, s0
	s_nop 0
	v_addc_co_u32_e32 v99, vcc, 0, v103, vcc
	flat_store_short v[98:99], v100

; DI bf16_t f2bf(float a) { return (bf16_t)(pk2(a, 0.f) & 0xffffu); }
;   DI void store(int m, int n, float a, float b, float c, float d) const {
;     int bb = m >> 13, s = m & (SEQ - 1);
;     if (n >= C_VS && n < C_KW) { int e = n - C_VS; bf16_t* p = vsT + ((size_t)(bb * 128 + e)) * SEQ + s; p[0] = f2bf(a); p[SEQ] = f2bf(b); p[2 * SEQ] = f2bf(c); p[3 * SEQ] = f2bf(d); }
.LBB0_369:
	s_andn2_saveexec_b64 s[18:19], s[18:19]
	s_cbranch_execz .LBB0_371
	v_lshrrev_b32_e32 v100, 14, v148
	v_and_b32_e32 v102, 0x1c0, v100
	v_lshlrev_b32_e32 v102, 14, v102
	v_bfe_u32 v101, v100, 4, 2
	v_lshl_or_b32 v102, v101, 11, v102
	v_and_b32_e32 v101, 15, v100
	v_lshl_or_b32 v102, v101, 6, v102
	v_lshrrev_b32_e32 v101, 6, v99
	v_lshl_or_b32 v102, v101, 13, v102
	v_bfe_u32 v101, v99, 5, 1
	v_lshl_or_b32 v102, v101, 10, v102
	v_and_b32_e32 v101, 31, v99
	v_lshl_or_b32 v102, v101, 1, v102
	v_mov_b32_e32 v103, v1
	v_lshl_add_u64 v[100:101], s[10:11], 0, v[102:103]
	v_cvt_pk_bf16_f32 v94, v94, s0
	flat_store_short v[100:101], v94
	v_add_co_u32_e32 v94, vcc, 0x40, v100
	v_cvt_pk_bf16_f32 v102, v95, s0
	s_nop 0
	v_addc_co_u32_e32 v95, vcc, 0, v101, vcc
	flat_store_short v[94:95], v102
	v_add_co_u32_e32 v94, vcc, 0x80, v100
	v_cvt_pk_bf16_f32 v96, v96, s0
	s_nop 0
	v_addc_co_u32_e32 v95, vcc, 0, v101, vcc
	flat_store_short v[94:95], v96
	v_add_co_u32_e32 v94, vcc, 0xc0, v100
	v_cvt_pk_bf16_f32 v96, v97, s0
	s_nop 0
	v_addc_co_u32_e32 v95, vcc, 0, v101, vcc
	flat_store_short v[94:95], v96

; DI bf16_t f2bf(float a) { return (bf16_t)(pk2(a, 0.f) & 0xffffu); }
;   DI void store(int m, int n, float a, float b, float c, float d) const {
;     int bb = m >> 13, s = m & (SEQ - 1);
;     if (n >= C_VS && n < C_KW) { int e = n - C_VS; bf16_t* p = vsT + ((size_t)(bb * 128 + e)) * SEQ + s; p[0] = f2bf(a); p[SEQ] = f2bf(b); p[2 * SEQ] = f2bf(c); p[3 * SEQ] = f2bf(d); }
.LBB0_377:
	s_andn2_saveexec_b64 s[6:7], s[6:7]
	s_cbranch_execz .LBB0_379
	v_lshrrev_b32_e32 v94, 14, v132
	v_and_b32_e32 v96, 0x1c0, v94
	v_lshlrev_b32_e32 v96, 14, v96
	v_bfe_u32 v95, v94, 4, 2
	v_lshl_or_b32 v96, v95, 11, v96
	v_and_b32_e32 v95, 15, v94
	v_lshl_or_b32 v96, v95, 6, v96
	v_lshrrev_b32_e32 v95, 6, v99
	v_lshl_or_b32 v96, v95, 13, v96
	v_bfe_u32 v95, v99, 5, 1
	v_lshl_or_b32 v96, v95, 10, v96
	v_and_b32_e32 v95, 31, v99
	v_lshl_or_b32 v96, v95, 1, v96
	v_mov_b32_e32 v97, v1
	v_lshl_add_u64 v[94:95], s[10:11], 0, v[96:97]
	v_cvt_pk_bf16_f32 v90, v90, s0
	flat_store_short v[94:95], v90
	v_add_co_u32_e32 v90, vcc, 0x40, v94
	v_cvt_pk_bf16_f32 v96, v91, s0
	s_nop 0
	v_addc_co_u32_e32 v91, vcc, 0, v95, vcc
	flat_store_short v[90:91], v96
	v_add_co_u32_e32 v90, vcc, 0x80, v94
	v_cvt_pk_bf16_f32 v92, v92, s0
	s_nop 0
	v_addc_co_u32_e32 v91, vcc, 0, v95, vcc
	flat_store_short v[90:91], v92
	v_add_co_u32_e32 v90, vcc, 0xc0, v94
	v_cvt_pk_bf16_f32 v92, v93, s0
	s_nop 0
	v_addc_co_u32_e32 v91, vcc, 0, v95, vcc
	flat_store_short v[90:91], v92

; DI bf16_t f2bf(float a) { return (bf16_t)(pk2(a, 0.f) & 0xffffu); }
;   DI void store(int m, int n, float a, float b, float c, float d) const {
;     int bb = m >> 13, s = m & (SEQ - 1);
;     if (n >= C_VS && n < C_KW) { int e = n - C_VS; bf16_t* p = vsT + ((size_t)(bb * 128 + e)) * SEQ + s; p[0] = f2bf(a); p[SEQ] = f2bf(b); p[2 * SEQ] = f2bf(c); p[3 * SEQ] = f2bf(d); }
.LBB0_392:
	s_andn2_saveexec_b64 s[18:19], s[18:19]
	s_cbranch_execz .LBB0_394
	v_lshrrev_b32_e32 v92, 14, v148
	v_and_b32_e32 v94, 0x1c0, v92
	v_lshlrev_b32_e32 v94, 14, v94
	v_bfe_u32 v93, v92, 4, 2
	v_lshl_or_b32 v94, v93, 11, v94
	v_and_b32_e32 v93, 15, v92
	v_lshl_or_b32 v94, v93, 6, v94
	v_lshrrev_b32_e32 v93, 6, v91
	v_lshl_or_b32 v94, v93, 13, v94
	v_bfe_u32 v93, v91, 5, 1
	v_lshl_or_b32 v94, v93, 10, v94
	v_and_b32_e32 v93, 31, v91
	v_lshl_or_b32 v94, v93, 1, v94
	v_mov_b32_e32 v95, v1
	v_lshl_add_u64 v[92:93], s[10:11], 0, v[94:95]
	v_cvt_pk_bf16_f32 v86, v86, s0
	flat_store_short v[92:93], v86
	v_add_co_u32_e32 v86, vcc, 0x40, v92
	v_cvt_pk_bf16_f32 v94, v87, s0
	s_nop 0
	v_addc_co_u32_e32 v87, vcc, 0, v93, vcc
	flat_store_short v[86:87], v94
	v_add_co_u32_e32 v86, vcc, 0x80, v92
	v_cvt_pk_bf16_f32 v88, v88, s0
	s_nop 0
	v_addc_co_u32_e32 v87, vcc, 0, v93, vcc
	flat_store_short v[86:87], v88
	v_add_co_u32_e32 v86, vcc, 0xc0, v92
	v_cvt_pk_bf16_f32 v88, v89, s0
	s_nop 0
	v_addc_co_u32_e32 v87, vcc, 0, v93, vcc
	flat_store_short v[86:87], v88

; DI bf16_t f2bf(float a) { return (bf16_t)(pk2(a, 0.f) & 0xffffu); }
;   DI void store(int m, int n, float a, float b, float c, float d) const {
;     int bb = m >> 13, s = m & (SEQ - 1);
;     if (n >= C_VS && n < C_KW) { int e = n - C_VS; bf16_t* p = vsT + ((size_t)(bb * 128 + e)) * SEQ + s; p[0] = f2bf(a); p[SEQ] = f2bf(b); p[2 * SEQ] = f2bf(c); p[3 * SEQ] = f2bf(d); }
.LBB0_400:
	s_andn2_saveexec_b64 s[6:7], s[6:7]
	s_cbranch_execz .LBB0_402
	v_lshrrev_b32_e32 v86, 14, v132
	v_and_b32_e32 v88, 0x1c0, v86
	v_lshlrev_b32_e32 v88, 14, v88
	v_bfe_u32 v87, v86, 4, 2
	v_lshl_or_b32 v88, v87, 11, v88
	v_and_b32_e32 v87, 15, v86
	v_lshl_or_b32 v88, v87, 6, v88
	v_lshrrev_b32_e32 v87, 6, v91
	v_lshl_or_b32 v88, v87, 13, v88
	v_bfe_u32 v87, v91, 5, 1
	v_lshl_or_b32 v88, v87, 10, v88
	v_and_b32_e32 v87, 31, v91
	v_lshl_or_b32 v88, v87, 1, v88
	v_mov_b32_e32 v89, v1
	v_lshl_add_u64 v[86:87], s[10:11], 0, v[88:89]
	v_cvt_pk_bf16_f32 v82, v82, s0
	flat_store_short v[86:87], v82
	v_add_co_u32_e32 v82, vcc, 0x40, v86
	v_cvt_pk_bf16_f32 v88, v83, s0
	s_nop 0
	v_addc_co_u32_e32 v83, vcc, 0, v87, vcc
	flat_store_short v[82:83], v88
	v_add_co_u32_e32 v82, vcc, 0x80, v86
	v_cvt_pk_bf16_f32 v84, v84, s0
	s_nop 0
	v_addc_co_u32_e32 v83, vcc, 0, v87, vcc
	flat_store_short v[82:83], v84
	v_add_co_u32_e32 v82, vcc, 0xc0, v86
	v_cvt_pk_bf16_f32 v84, v85, s0
	s_nop 0
	v_addc_co_u32_e32 v83, vcc, 0, v87, vcc
	flat_store_short v[82:83], v84

; DI bf16_t f2bf(float a) { return (bf16_t)(pk2(a, 0.f) & 0xffffu); }
;   DI void store(int m, int n, float a, float b, float c, float d) const {
;     int bb = m >> 13, s = m & (SEQ - 1);
;     if (n >= C_VS && n < C_KW) { int e = n - C_VS; bf16_t* p = vsT + ((size_t)(bb * 128 + e)) * SEQ + s; p[0] = f2bf(a); p[SEQ] = f2bf(b); p[2 * SEQ] = f2bf(c); p[3 * SEQ] = f2bf(d); }
.LBB0_415:
	s_andn2_saveexec_b64 s[18:19], s[18:19]
	s_cbranch_execz .LBB0_417
	v_lshrrev_b32_e32 v84, 14, v148
	v_and_b32_e32 v86, 0x1c0, v84
	v_lshlrev_b32_e32 v86, 14, v86
	v_bfe_u32 v85, v84, 4, 2
	v_lshl_or_b32 v86, v85, 11, v86
	v_and_b32_e32 v85, 15, v84
	v_lshl_or_b32 v86, v85, 6, v86
	v_lshrrev_b32_e32 v85, 6, v83
	v_lshl_or_b32 v86, v85, 13, v86
	v_bfe_u32 v85, v83, 5, 1
	v_lshl_or_b32 v86, v85, 10, v86
	v_and_b32_e32 v85, 31, v83
	v_lshl_or_b32 v86, v85, 1, v86
	v_mov_b32_e32 v87, v1
	v_lshl_add_u64 v[84:85], s[10:11], 0, v[86:87]
	v_cvt_pk_bf16_f32 v78, v78, s0
	flat_store_short v[84:85], v78
	v_add_co_u32_e32 v78, vcc, 0x40, v84
	v_cvt_pk_bf16_f32 v86, v79, s0
	s_nop 0
	v_addc_co_u32_e32 v79, vcc, 0, v85, vcc
	flat_store_short v[78:79], v86
	v_add_co_u32_e32 v78, vcc, 0x80, v84
	v_cvt_pk_bf16_f32 v80, v80, s0
	s_nop 0
	v_addc_co_u32_e32 v79, vcc, 0, v85, vcc
	flat_store_short v[78:79], v80
	v_add_co_u32_e32 v78, vcc, 0xc0, v84
	v_cvt_pk_bf16_f32 v80, v81, s0
	s_nop 0
	v_addc_co_u32_e32 v79, vcc, 0, v85, vcc
	flat_store_short v[78:79], v80

; DI bf16_t f2bf(float a) { return (bf16_t)(pk2(a, 0.f) & 0xffffu); }
;   DI void store(int m, int n, float a, float b, float c, float d) const {
;     int bb = m >> 13, s = m & (SEQ - 1);
;     if (n >= C_VS && n < C_KW) { int e = n - C_VS; bf16_t* p = vsT + ((size_t)(bb * 128 + e)) * SEQ + s; p[0] = f2bf(a); p[SEQ] = f2bf(b); p[2 * SEQ] = f2bf(c); p[3 * SEQ] = f2bf(d); }
.LBB0_423:
	s_andn2_saveexec_b64 s[6:7], s[6:7]
	s_cbranch_execz .LBB0_425
	v_lshrrev_b32_e32 v78, 14, v132
	v_and_b32_e32 v80, 0x1c0, v78
	v_lshlrev_b32_e32 v80, 14, v80
	v_bfe_u32 v79, v78, 4, 2
	v_lshl_or_b32 v80, v79, 11, v80
	v_and_b32_e32 v79, 15, v78
	v_lshl_or_b32 v80, v79, 6, v80
	v_lshrrev_b32_e32 v79, 6, v83
	v_lshl_or_b32 v80, v79, 13, v80
	v_bfe_u32 v79, v83, 5, 1
	v_lshl_or_b32 v80, v79, 10, v80
	v_and_b32_e32 v79, 31, v83
	v_lshl_or_b32 v80, v79, 1, v80
	v_mov_b32_e32 v81, v1
	v_lshl_add_u64 v[78:79], s[10:11], 0, v[80:81]
	v_cvt_pk_bf16_f32 v74, v74, s0
	flat_store_short v[78:79], v74
	v_add_co_u32_e32 v74, vcc, 0x40, v78
	v_cvt_pk_bf16_f32 v80, v75, s0
	s_nop 0
	v_addc_co_u32_e32 v75, vcc, 0, v79, vcc
	flat_store_short v[74:75], v80
	v_add_co_u32_e32 v74, vcc, 0x80, v78
	v_cvt_pk_bf16_f32 v76, v76, s0
	s_nop 0
	v_addc_co_u32_e32 v75, vcc, 0, v79, vcc
	flat_store_short v[74:75], v76
	v_add_co_u32_e32 v74, vcc, 0xc0, v78
	v_cvt_pk_bf16_f32 v76, v77, s0
	s_nop 0
	v_addc_co_u32_e32 v75, vcc, 0, v79, vcc
	flat_store_short v[74:75], v76

; DI bf16_t f2bf(float a) { return (bf16_t)(pk2(a, 0.f) & 0xffffu); }
;   DI void store(int m, int n, float a, float b, float c, float d) const {
;     int bb = m >> 13, s = m & (SEQ - 1);
;     if (n >= C_VS && n < C_KW) { int e = n - C_VS; bf16_t* p = vsT + ((size_t)(bb * 128 + e)) * SEQ + s; p[0] = f2bf(a); p[SEQ] = f2bf(b); p[2 * SEQ] = f2bf(c); p[3 * SEQ] = f2bf(d); }
.LBB0_438:
	s_andn2_saveexec_b64 s[16:17], s[16:17]
	s_cbranch_execz .LBB0_440
	v_lshrrev_b32_e32 v76, 14, v148
	v_and_b32_e32 v78, 0x1c0, v76
	v_lshlrev_b32_e32 v78, 14, v78
	v_bfe_u32 v77, v76, 4, 2
	v_lshl_or_b32 v78, v77, 11, v78
	v_and_b32_e32 v77, 15, v76
	v_lshl_or_b32 v78, v77, 6, v78
	v_lshrrev_b32_e32 v77, 6, v75
	v_lshl_or_b32 v78, v77, 13, v78
	v_bfe_u32 v77, v75, 5, 1
	v_lshl_or_b32 v78, v77, 10, v78
	v_and_b32_e32 v77, 31, v75
	v_lshl_or_b32 v78, v77, 1, v78
	v_mov_b32_e32 v79, v1
	v_lshl_add_u64 v[76:77], s[10:11], 0, v[78:79]
	v_cvt_pk_bf16_f32 v70, v70, s0
	flat_store_short v[76:77], v70
	v_add_co_u32_e32 v70, vcc, 0x40, v76
	v_cvt_pk_bf16_f32 v78, v71, s0
	s_nop 0
	v_addc_co_u32_e32 v71, vcc, 0, v77, vcc
	flat_store_short v[70:71], v78
	v_add_co_u32_e32 v70, vcc, 0x80, v76
	v_cvt_pk_bf16_f32 v72, v72, s0
	s_nop 0
	v_addc_co_u32_e32 v71, vcc, 0, v77, vcc
	flat_store_short v[70:71], v72
	v_add_co_u32_e32 v70, vcc, 0xc0, v76
	v_cvt_pk_bf16_f32 v72, v73, s0
	s_nop 0
	v_addc_co_u32_e32 v71, vcc, 0, v77, vcc
	flat_store_short v[70:71], v72

; DI bf16_t f2bf(float a) { return (bf16_t)(pk2(a, 0.f) & 0xffffu); }
;   DI void store(int m, int n, float a, float b, float c, float d) const {
;     int bb = m >> 13, s = m & (SEQ - 1);
;     if (n >= C_VS && n < C_KW) { int e = n - C_VS; bf16_t* p = vsT + ((size_t)(bb * 128 + e)) * SEQ + s; p[0] = f2bf(a); p[SEQ] = f2bf(b); p[2 * SEQ] = f2bf(c); p[3 * SEQ] = f2bf(d); }
.LBB0_446:
	s_andn2_saveexec_b64 s[4:5], s[4:5]
	s_cbranch_execz .LBB0_448
	v_lshrrev_b32_e32 v70, 14, v132
	v_and_b32_e32 v72, 0x1c0, v70
	v_lshlrev_b32_e32 v72, 14, v72
	v_bfe_u32 v71, v70, 4, 2
	v_lshl_or_b32 v72, v71, 11, v72
	v_and_b32_e32 v71, 15, v70
	v_lshl_or_b32 v72, v71, 6, v72
	v_lshrrev_b32_e32 v71, 6, v75
	v_lshl_or_b32 v72, v71, 13, v72
	v_bfe_u32 v71, v75, 5, 1
	v_lshl_or_b32 v72, v71, 10, v72
	v_and_b32_e32 v71, 31, v75
	v_lshl_or_b32 v72, v71, 1, v72
	v_mov_b32_e32 v73, v1
	v_lshl_add_u64 v[70:71], s[10:11], 0, v[72:73]
	v_cvt_pk_bf16_f32 v66, v66, s0
	flat_store_short v[70:71], v66
	v_add_co_u32_e32 v66, vcc, 0x40, v70
	v_cvt_pk_bf16_f32 v72, v67, s0
	s_nop 0
	v_addc_co_u32_e32 v67, vcc, 0, v71, vcc
	flat_store_short v[66:67], v72
	v_add_co_u32_e32 v66, vcc, 0x80, v70
	v_cvt_pk_bf16_f32 v68, v68, s0
	s_nop 0
	v_addc_co_u32_e32 v67, vcc, 0, v71, vcc
	flat_store_short v[66:67], v68
	v_add_co_u32_e32 v66, vcc, 0xc0, v70
	v_cvt_pk_bf16_f32 v68, v69, s0
	s_nop 0
	v_addc_co_u32_e32 v67, vcc, 0, v71, vcc
	flat_store_short v[66:67], v68

; DI bf16_t f2bf(float a) { return (bf16_t)(pk2(a, 0.f) & 0xffffu); }
;   DI void store(int m, int n, float a, float b, float c, float d) const {
;     int bb = m >> 13, s = m & (SEQ - 1);
;     if (n >= C_VS && n < C_KW) { int e = n - C_VS; bf16_t* p = vsT + ((size_t)(bb * 128 + e)) * SEQ + s; p[0] = f2bf(a); p[SEQ] = f2bf(b); p[2 * SEQ] = f2bf(c); p[3 * SEQ] = f2bf(d); }
.LBB0_461:
	s_andn2_saveexec_b64 s[18:19], s[18:19]
	s_cbranch_execz .LBB0_463
	v_lshrrev_b32_e32 v76, 14, v70
	v_and_b32_e32 v78, 0x1c0, v76
	v_lshlrev_b32_e32 v78, 14, v78
	v_bfe_u32 v77, v76, 4, 2
	v_lshl_or_b32 v78, v77, 11, v78
	v_and_b32_e32 v77, 15, v76
	v_lshl_or_b32 v78, v77, 6, v78
	v_lshrrev_b32_e32 v77, 6, v74
	v_lshl_or_b32 v78, v77, 13, v78
	v_bfe_u32 v77, v74, 5, 1
	v_lshl_or_b32 v78, v77, 10, v78
	v_and_b32_e32 v77, 31, v74
	v_lshl_or_b32 v78, v77, 1, v78
	v_mov_b32_e32 v79, v1
	v_lshl_add_u64 v[76:77], s[10:11], 0, v[78:79]
	v_cvt_pk_bf16_f32 v62, v62, s0
	flat_store_short v[76:77], v62
	v_add_co_u32_e32 v62, vcc, 0x40, v76
	v_cvt_pk_bf16_f32 v75, v63, s0
	s_nop 0
	v_addc_co_u32_e32 v63, vcc, 0, v77, vcc
	flat_store_short v[62:63], v75
	v_add_co_u32_e32 v62, vcc, 0x80, v76
	v_cvt_pk_bf16_f32 v64, v64, s0
	s_nop 0
	v_addc_co_u32_e32 v63, vcc, 0, v77, vcc
	flat_store_short v[62:63], v64
	v_add_co_u32_e32 v62, vcc, 0xc0, v76
	v_cvt_pk_bf16_f32 v64, v65, s0
	s_nop 0
	v_addc_co_u32_e32 v63, vcc, 0, v77, vcc
	flat_store_short v[62:63], v64

; DI bf16_t f2bf(float a) { return (bf16_t)(pk2(a, 0.f) & 0xffffu); }
;   DI void store(int m, int n, float a, float b, float c, float d) const {
;     int bb = m >> 13, s = m & (SEQ - 1);
;     if (n >= C_VS && n < C_KW) { int e = n - C_VS; bf16_t* p = vsT + ((size_t)(bb * 128 + e)) * SEQ + s; p[0] = f2bf(a); p[SEQ] = f2bf(b); p[2 * SEQ] = f2bf(c); p[3 * SEQ] = f2bf(d); }
.LBB0_469:
	s_andn2_saveexec_b64 s[6:7], s[6:7]
	s_cbranch_execz .LBB0_471
	v_lshrrev_b32_e32 v62, 14, v66
	v_and_b32_e32 v64, 0x1c0, v62
	v_lshlrev_b32_e32 v64, 14, v64
	v_bfe_u32 v63, v62, 4, 2
	v_lshl_or_b32 v64, v63, 11, v64
	v_and_b32_e32 v63, 15, v62
	v_lshl_or_b32 v64, v63, 6, v64
	v_lshrrev_b32_e32 v63, 6, v74
	v_lshl_or_b32 v64, v63, 13, v64
	v_bfe_u32 v63, v74, 5, 1
	v_lshl_or_b32 v64, v63, 10, v64
	v_and_b32_e32 v63, 31, v74
	v_lshl_or_b32 v64, v63, 1, v64
	v_mov_b32_e32 v65, v1
	v_lshl_add_u64 v[62:63], s[10:11], 0, v[64:65]
	v_cvt_pk_bf16_f32 v58, v58, s0
	flat_store_short v[62:63], v58
	v_add_co_u32_e32 v58, vcc, 0x40, v62
	v_cvt_pk_bf16_f32 v64, v59, s0
	s_nop 0
	v_addc_co_u32_e32 v59, vcc, 0, v63, vcc
	flat_store_short v[58:59], v64
	v_add_co_u32_e32 v58, vcc, 0x80, v62
	v_cvt_pk_bf16_f32 v60, v60, s0
	s_nop 0
	v_addc_co_u32_e32 v59, vcc, 0, v63, vcc
	flat_store_short v[58:59], v60
	v_add_co_u32_e32 v58, vcc, 0xc0, v62
	v_cvt_pk_bf16_f32 v60, v61, s0
	s_nop 0
	v_addc_co_u32_e32 v59, vcc, 0, v63, vcc
	flat_store_short v[58:59], v60

; DI bf16_t f2bf(float a) { return (bf16_t)(pk2(a, 0.f) & 0xffffu); }
;   DI void store(int m, int n, float a, float b, float c, float d) const {
;     int bb = m >> 13, s = m & (SEQ - 1);
;     if (n >= C_VS && n < C_KW) { int e = n - C_VS; bf16_t* p = vsT + ((size_t)(bb * 128 + e)) * SEQ + s; p[0] = f2bf(a); p[SEQ] = f2bf(b); p[2 * SEQ] = f2bf(c); p[3 * SEQ] = f2bf(d); }
.LBB0_484:
	s_andn2_saveexec_b64 s[18:19], s[18:19]
	s_cbranch_execz .LBB0_486
	v_lshrrev_b32_e32 v60, 14, v70
	v_and_b32_e32 v62, 0x1c0, v60
	v_lshlrev_b32_e32 v62, 14, v62
	v_bfe_u32 v61, v60, 4, 2
	v_lshl_or_b32 v62, v61, 11, v62
	v_and_b32_e32 v61, 15, v60
	v_lshl_or_b32 v62, v61, 6, v62
	v_lshrrev_b32_e32 v61, 6, v59
	v_lshl_or_b32 v62, v61, 13, v62
	v_bfe_u32 v61, v59, 5, 1
	v_lshl_or_b32 v62, v61, 10, v62
	v_and_b32_e32 v61, 31, v59
	v_lshl_or_b32 v62, v61, 1, v62
	v_mov_b32_e32 v63, v1
	v_lshl_add_u64 v[60:61], s[10:11], 0, v[62:63]
	v_cvt_pk_bf16_f32 v54, v54, s0
	flat_store_short v[60:61], v54
	v_add_co_u32_e32 v54, vcc, 0x40, v60
	v_cvt_pk_bf16_f32 v62, v55, s0
	s_nop 0
	v_addc_co_u32_e32 v55, vcc, 0, v61, vcc
	flat_store_short v[54:55], v62
	v_add_co_u32_e32 v54, vcc, 0x80, v60
	v_cvt_pk_bf16_f32 v56, v56, s0
	s_nop 0
	v_addc_co_u32_e32 v55, vcc, 0, v61, vcc
	flat_store_short v[54:55], v56
	v_add_co_u32_e32 v54, vcc, 0xc0, v60
	v_cvt_pk_bf16_f32 v56, v57, s0
	s_nop 0
	v_addc_co_u32_e32 v55, vcc, 0, v61, vcc
	flat_store_short v[54:55], v56

; DI bf16_t f2bf(float a) { return (bf16_t)(pk2(a, 0.f) & 0xffffu); }
;   DI void store(int m, int n, float a, float b, float c, float d) const {
;     int bb = m >> 13, s = m & (SEQ - 1);
;     if (n >= C_VS && n < C_KW) { int e = n - C_VS; bf16_t* p = vsT + ((size_t)(bb * 128 + e)) * SEQ + s; p[0] = f2bf(a); p[SEQ] = f2bf(b); p[2 * SEQ] = f2bf(c); p[3 * SEQ] = f2bf(d); }
.LBB0_492:
	s_andn2_saveexec_b64 s[6:7], s[6:7]
	s_cbranch_execz .LBB0_494
	v_lshrrev_b32_e32 v54, 14, v66
	v_and_b32_e32 v56, 0x1c0, v54
	v_lshlrev_b32_e32 v56, 14, v56
	v_bfe_u32 v55, v54, 4, 2
	v_lshl_or_b32 v56, v55, 11, v56
	v_and_b32_e32 v55, 15, v54
	v_lshl_or_b32 v56, v55, 6, v56
	v_lshrrev_b32_e32 v55, 6, v59
	v_lshl_or_b32 v56, v55, 13, v56
	v_bfe_u32 v55, v59, 5, 1
	v_lshl_or_b32 v56, v55, 10, v56
	v_and_b32_e32 v55, 31, v59
	v_lshl_or_b32 v56, v55, 1, v56
	v_mov_b32_e32 v57, v1
	v_lshl_add_u64 v[54:55], s[10:11], 0, v[56:57]
	v_cvt_pk_bf16_f32 v50, v50, s0
	flat_store_short v[54:55], v50
	v_add_co_u32_e32 v50, vcc, 0x40, v54
	v_cvt_pk_bf16_f32 v56, v51, s0
	s_nop 0
	v_addc_co_u32_e32 v51, vcc, 0, v55, vcc
	flat_store_short v[50:51], v56
	v_add_co_u32_e32 v50, vcc, 0x80, v54
	v_cvt_pk_bf16_f32 v52, v52, s0
	s_nop 0
	v_addc_co_u32_e32 v51, vcc, 0, v55, vcc
	flat_store_short v[50:51], v52
	v_add_co_u32_e32 v50, vcc, 0xc0, v54
	v_cvt_pk_bf16_f32 v52, v53, s0
	s_nop 0
	v_addc_co_u32_e32 v51, vcc, 0, v55, vcc
	flat_store_short v[50:51], v52

; DI bf16_t f2bf(float a) { return (bf16_t)(pk2(a, 0.f) & 0xffffu); }
;   DI void store(int m, int n, float a, float b, float c, float d) const {
;     int bb = m >> 13, s = m & (SEQ - 1);
;     if (n >= C_VS && n < C_KW) { int e = n - C_VS; bf16_t* p = vsT + ((size_t)(bb * 128 + e)) * SEQ + s; p[0] = f2bf(a); p[SEQ] = f2bf(b); p[2 * SEQ] = f2bf(c); p[3 * SEQ] = f2bf(d); }
.LBB0_507:
	s_andn2_saveexec_b64 s[18:19], s[18:19]
	s_cbranch_execz .LBB0_509
	v_lshrrev_b32_e32 v52, 14, v70
	v_and_b32_e32 v54, 0x1c0, v52
	v_lshlrev_b32_e32 v54, 14, v54
	v_bfe_u32 v53, v52, 4, 2
	v_lshl_or_b32 v54, v53, 11, v54
	v_and_b32_e32 v53, 15, v52
	v_lshl_or_b32 v54, v53, 6, v54
	v_lshrrev_b32_e32 v53, 6, v51
	v_lshl_or_b32 v54, v53, 13, v54
	v_bfe_u32 v53, v51, 5, 1
	v_lshl_or_b32 v54, v53, 10, v54
	v_and_b32_e32 v53, 31, v51
	v_lshl_or_b32 v54, v53, 1, v54
	v_mov_b32_e32 v55, v1
	v_lshl_add_u64 v[52:53], s[10:11], 0, v[54:55]
	v_cvt_pk_bf16_f32 v46, v46, s0
	flat_store_short v[52:53], v46
	v_add_co_u32_e32 v46, vcc, 0x40, v52
	v_cvt_pk_bf16_f32 v54, v47, s0
	s_nop 0
	v_addc_co_u32_e32 v47, vcc, 0, v53, vcc
	flat_store_short v[46:47], v54
	v_add_co_u32_e32 v46, vcc, 0x80, v52
	v_cvt_pk_bf16_f32 v48, v48, s0
	s_nop 0
	v_addc_co_u32_e32 v47, vcc, 0, v53, vcc
	flat_store_short v[46:47], v48
	v_add_co_u32_e32 v46, vcc, 0xc0, v52
	v_cvt_pk_bf16_f32 v48, v49, s0
	s_nop 0
	v_addc_co_u32_e32 v47, vcc, 0, v53, vcc
	flat_store_short v[46:47], v48

; DI bf16_t f2bf(float a) { return (bf16_t)(pk2(a, 0.f) & 0xffffu); }
;   DI void store(int m, int n, float a, float b, float c, float d) const {
;     int bb = m >> 13, s = m & (SEQ - 1);
;     if (n >= C_VS && n < C_KW) { int e = n - C_VS; bf16_t* p = vsT + ((size_t)(bb * 128 + e)) * SEQ + s; p[0] = f2bf(a); p[SEQ] = f2bf(b); p[2 * SEQ] = f2bf(c); p[3 * SEQ] = f2bf(d); }
.LBB0_515:
	s_andn2_saveexec_b64 s[6:7], s[6:7]
	s_cbranch_execz .LBB0_517
	v_lshrrev_b32_e32 v46, 14, v66
	v_and_b32_e32 v48, 0x1c0, v46
	v_lshlrev_b32_e32 v48, 14, v48
	v_bfe_u32 v47, v46, 4, 2
	v_lshl_or_b32 v48, v47, 11, v48
	v_and_b32_e32 v47, 15, v46
	v_lshl_or_b32 v48, v47, 6, v48
	v_lshrrev_b32_e32 v47, 6, v51
	v_lshl_or_b32 v48, v47, 13, v48
	v_bfe_u32 v47, v51, 5, 1
	v_lshl_or_b32 v48, v47, 10, v48
	v_and_b32_e32 v47, 31, v51
	v_lshl_or_b32 v48, v47, 1, v48
	v_mov_b32_e32 v49, v1
	v_lshl_add_u64 v[46:47], s[10:11], 0, v[48:49]
	v_cvt_pk_bf16_f32 v42, v42, s0
	flat_store_short v[46:47], v42
	v_add_co_u32_e32 v42, vcc, 0x40, v46
	v_cvt_pk_bf16_f32 v48, v43, s0
	s_nop 0
	v_addc_co_u32_e32 v43, vcc, 0, v47, vcc
	flat_store_short v[42:43], v48
	v_add_co_u32_e32 v42, vcc, 0x80, v46
	v_cvt_pk_bf16_f32 v44, v44, s0
	s_nop 0
	v_addc_co_u32_e32 v43, vcc, 0, v47, vcc
	flat_store_short v[42:43], v44
	v_add_co_u32_e32 v42, vcc, 0xc0, v46
	v_cvt_pk_bf16_f32 v44, v45, s0
	s_nop 0
	v_addc_co_u32_e32 v43, vcc, 0, v47, vcc
	flat_store_short v[42:43], v44

; DI bf16_t f2bf(float a) { return (bf16_t)(pk2(a, 0.f) & 0xffffu); }
;   DI void store(int m, int n, float a, float b, float c, float d) const {
;     int bb = m >> 13, s = m & (SEQ - 1);
;     if (n >= C_VS && n < C_KW) { int e = n - C_VS; bf16_t* p = vsT + ((size_t)(bb * 128 + e)) * SEQ + s; p[0] = f2bf(a); p[SEQ] = f2bf(b); p[2 * SEQ] = f2bf(c); p[3 * SEQ] = f2bf(d); }
.LBB0_530:
	s_andn2_saveexec_b64 s[18:19], s[18:19]
	s_cbranch_execz .LBB0_532
	v_lshrrev_b32_e32 v44, 14, v70
	v_and_b32_e32 v46, 0x1c0, v44
	v_lshlrev_b32_e32 v46, 14, v46
	v_bfe_u32 v45, v44, 4, 2
	v_lshl_or_b32 v46, v45, 11, v46
	v_and_b32_e32 v45, 15, v44
	v_lshl_or_b32 v46, v45, 6, v46
	v_lshrrev_b32_e32 v45, 6, v43
	v_lshl_or_b32 v46, v45, 13, v46
	v_bfe_u32 v45, v43, 5, 1
	v_lshl_or_b32 v46, v45, 10, v46
	v_and_b32_e32 v45, 31, v43
	v_lshl_or_b32 v46, v45, 1, v46
	v_mov_b32_e32 v47, v1
	v_lshl_add_u64 v[44:45], s[10:11], 0, v[46:47]
	v_cvt_pk_bf16_f32 v38, v38, s0
	flat_store_short v[44:45], v38
	v_add_co_u32_e32 v38, vcc, 0x40, v44
	v_cvt_pk_bf16_f32 v46, v39, s0
	s_nop 0
	v_addc_co_u32_e32 v39, vcc, 0, v45, vcc
	flat_store_short v[38:39], v46
	v_add_co_u32_e32 v38, vcc, 0x80, v44
	v_cvt_pk_bf16_f32 v40, v40, s0
	s_nop 0
	v_addc_co_u32_e32 v39, vcc, 0, v45, vcc
	flat_store_short v[38:39], v40
	v_add_co_u32_e32 v38, vcc, 0xc0, v44
	v_cvt_pk_bf16_f32 v40, v41, s0
	s_nop 0
	v_addc_co_u32_e32 v39, vcc, 0, v45, vcc
	flat_store_short v[38:39], v40

; DI bf16_t f2bf(float a) { return (bf16_t)(pk2(a, 0.f) & 0xffffu); }
;   DI void store(int m, int n, float a, float b, float c, float d) const {
;     int bb = m >> 13, s = m & (SEQ - 1);
;     if (n >= C_VS && n < C_KW) { int e = n - C_VS; bf16_t* p = vsT + ((size_t)(bb * 128 + e)) * SEQ + s; p[0] = f2bf(a); p[SEQ] = f2bf(b); p[2 * SEQ] = f2bf(c); p[3 * SEQ] = f2bf(d); }
.LBB0_538:
	s_andn2_saveexec_b64 s[6:7], s[6:7]
	s_cbranch_execz .LBB0_540
	v_lshrrev_b32_e32 v38, 14, v66
	v_and_b32_e32 v40, 0x1c0, v38
	v_lshlrev_b32_e32 v40, 14, v40
	v_bfe_u32 v39, v38, 4, 2
	v_lshl_or_b32 v40, v39, 11, v40
	v_and_b32_e32 v39, 15, v38
	v_lshl_or_b32 v40, v39, 6, v40
	v_lshrrev_b32_e32 v39, 6, v43
	v_lshl_or_b32 v40, v39, 13, v40
	v_bfe_u32 v39, v43, 5, 1
	v_lshl_or_b32 v40, v39, 10, v40
	v_and_b32_e32 v39, 31, v43
	v_lshl_or_b32 v40, v39, 1, v40
	v_mov_b32_e32 v41, v1
	v_lshl_add_u64 v[38:39], s[10:11], 0, v[40:41]
	v_cvt_pk_bf16_f32 v34, v34, s0
	flat_store_short v[38:39], v34
	v_add_co_u32_e32 v34, vcc, 0x40, v38
	v_cvt_pk_bf16_f32 v40, v35, s0
	s_nop 0
	v_addc_co_u32_e32 v35, vcc, 0, v39, vcc
	flat_store_short v[34:35], v40
	v_add_co_u32_e32 v34, vcc, 0x80, v38
	v_cvt_pk_bf16_f32 v36, v36, s0
	s_nop 0
	v_addc_co_u32_e32 v35, vcc, 0, v39, vcc
	flat_store_short v[34:35], v36
	v_add_co_u32_e32 v34, vcc, 0xc0, v38
	v_cvt_pk_bf16_f32 v36, v37, s0
	s_nop 0
	v_addc_co_u32_e32 v35, vcc, 0, v39, vcc
	flat_store_short v[34:35], v36

; DI bf16_t f2bf(float a) { return (bf16_t)(pk2(a, 0.f) & 0xffffu); }
;   DI void store(int m, int n, float a, float b, float c, float d) const {
;     int bb = m >> 13, s = m & (SEQ - 1);
;     if (n >= C_VS && n < C_KW) { int e = n - C_VS; bf16_t* p = vsT + ((size_t)(bb * 128 + e)) * SEQ + s; p[0] = f2bf(a); p[SEQ] = f2bf(b); p[2 * SEQ] = f2bf(c); p[3 * SEQ] = f2bf(d); }
.LBB0_553:
	s_andn2_saveexec_b64 s[18:19], s[18:19]
	s_cbranch_execz .LBB0_555
	v_lshrrev_b32_e32 v36, 14, v70
	v_and_b32_e32 v38, 0x1c0, v36
	v_lshlrev_b32_e32 v38, 14, v38
	v_bfe_u32 v37, v36, 4, 2
	v_lshl_or_b32 v38, v37, 11, v38
	v_and_b32_e32 v37, 15, v36
	v_lshl_or_b32 v38, v37, 6, v38
	v_lshrrev_b32_e32 v37, 6, v35
	v_lshl_or_b32 v38, v37, 13, v38
	v_bfe_u32 v37, v35, 5, 1
	v_lshl_or_b32 v38, v37, 10, v38
	v_and_b32_e32 v37, 31, v35
	v_lshl_or_b32 v38, v37, 1, v38
	v_mov_b32_e32 v39, v1
	v_lshl_add_u64 v[36:37], s[10:11], 0, v[38:39]
	v_cvt_pk_bf16_f32 v30, v30, s0
	flat_store_short v[36:37], v30
	v_add_co_u32_e32 v30, vcc, 0x40, v36
	v_cvt_pk_bf16_f32 v38, v31, s0
	s_nop 0
	v_addc_co_u32_e32 v31, vcc, 0, v37, vcc
	flat_store_short v[30:31], v38
	v_add_co_u32_e32 v30, vcc, 0x80, v36
	v_cvt_pk_bf16_f32 v32, v32, s0
	s_nop 0
	v_addc_co_u32_e32 v31, vcc, 0, v37, vcc
	flat_store_short v[30:31], v32
	v_add_co_u32_e32 v30, vcc, 0xc0, v36
	v_cvt_pk_bf16_f32 v32, v33, s0
	s_nop 0
	v_addc_co_u32_e32 v31, vcc, 0, v37, vcc
	flat_store_short v[30:31], v32

; DI bf16_t f2bf(float a) { return (bf16_t)(pk2(a, 0.f) & 0xffffu); }
;   DI void store(int m, int n, float a, float b, float c, float d) const {
;     int bb = m >> 13, s = m & (SEQ - 1);
;     if (n >= C_VS && n < C_KW) { int e = n - C_VS; bf16_t* p = vsT + ((size_t)(bb * 128 + e)) * SEQ + s; p[0] = f2bf(a); p[SEQ] = f2bf(b); p[2 * SEQ] = f2bf(c); p[3 * SEQ] = f2bf(d); }
.LBB0_561:
	s_andn2_saveexec_b64 s[6:7], s[6:7]
	s_cbranch_execz .LBB0_563
	v_lshrrev_b32_e32 v30, 14, v66
	v_and_b32_e32 v32, 0x1c0, v30
	v_lshlrev_b32_e32 v32, 14, v32
	v_bfe_u32 v31, v30, 4, 2
	v_lshl_or_b32 v32, v31, 11, v32
	v_and_b32_e32 v31, 15, v30
	v_lshl_or_b32 v32, v31, 6, v32
	v_lshrrev_b32_e32 v31, 6, v35
	v_lshl_or_b32 v32, v31, 13, v32
	v_bfe_u32 v31, v35, 5, 1
	v_lshl_or_b32 v32, v31, 10, v32
	v_and_b32_e32 v31, 31, v35
	v_lshl_or_b32 v32, v31, 1, v32
	v_mov_b32_e32 v33, v1
	v_lshl_add_u64 v[30:31], s[10:11], 0, v[32:33]
	v_cvt_pk_bf16_f32 v26, v26, s0
	flat_store_short v[30:31], v26
	v_add_co_u32_e32 v26, vcc, 0x40, v30
	v_cvt_pk_bf16_f32 v32, v27, s0
	s_nop 0
	v_addc_co_u32_e32 v27, vcc, 0, v31, vcc
	flat_store_short v[26:27], v32
	v_add_co_u32_e32 v26, vcc, 0x80, v30
	v_cvt_pk_bf16_f32 v28, v28, s0
	s_nop 0
	v_addc_co_u32_e32 v27, vcc, 0, v31, vcc
	flat_store_short v[26:27], v28
	v_add_co_u32_e32 v26, vcc, 0xc0, v30
	v_cvt_pk_bf16_f32 v28, v29, s0
	s_nop 0
	v_addc_co_u32_e32 v27, vcc, 0, v31, vcc
	flat_store_short v[26:27], v28

; DI bf16_t f2bf(float a) { return (bf16_t)(pk2(a, 0.f) & 0xffffu); }
;   DI void store(int m, int n, float a, float b, float c, float d) const {
;     int bb = m >> 13, s = m & (SEQ - 1);
;     if (n >= C_VS && n < C_KW) { int e = n - C_VS; bf16_t* p = vsT + ((size_t)(bb * 128 + e)) * SEQ + s; p[0] = f2bf(a); p[SEQ] = f2bf(b); p[2 * SEQ] = f2bf(c); p[3 * SEQ] = f2bf(d); }
.LBB0_576:
	s_andn2_saveexec_b64 s[18:19], s[18:19]
	s_cbranch_execz .LBB0_578
	v_lshrrev_b32_e32 v28, 14, v70
	v_and_b32_e32 v30, 0x1c0, v28
	v_lshlrev_b32_e32 v30, 14, v30
	v_bfe_u32 v29, v28, 4, 2
	v_lshl_or_b32 v30, v29, 11, v30
	v_and_b32_e32 v29, 15, v28
	v_lshl_or_b32 v30, v29, 6, v30
	v_lshrrev_b32_e32 v29, 6, v27
	v_lshl_or_b32 v30, v29, 13, v30
	v_bfe_u32 v29, v27, 5, 1
	v_lshl_or_b32 v30, v29, 10, v30
	v_and_b32_e32 v29, 31, v27
	v_lshl_or_b32 v30, v29, 1, v30
	v_mov_b32_e32 v31, v1
	v_lshl_add_u64 v[28:29], s[10:11], 0, v[30:31]
	v_cvt_pk_bf16_f32 v22, v22, s0
	flat_store_short v[28:29], v22
	v_add_co_u32_e32 v22, vcc, 0x40, v28
	v_cvt_pk_bf16_f32 v30, v23, s0
	s_nop 0
	v_addc_co_u32_e32 v23, vcc, 0, v29, vcc
	flat_store_short v[22:23], v30
	v_add_co_u32_e32 v22, vcc, 0x80, v28
	v_cvt_pk_bf16_f32 v24, v24, s0
	s_nop 0
	v_addc_co_u32_e32 v23, vcc, 0, v29, vcc
	flat_store_short v[22:23], v24
	v_add_co_u32_e32 v22, vcc, 0xc0, v28
	v_cvt_pk_bf16_f32 v24, v25, s0
	s_nop 0
	v_addc_co_u32_e32 v23, vcc, 0, v29, vcc
	flat_store_short v[22:23], v24

; DI bf16_t f2bf(float a) { return (bf16_t)(pk2(a, 0.f) & 0xffffu); }
;   DI void store(int m, int n, float a, float b, float c, float d) const {
;     int bb = m >> 13, s = m & (SEQ - 1);
;     if (n >= C_VS && n < C_KW) { int e = n - C_VS; bf16_t* p = vsT + ((size_t)(bb * 128 + e)) * SEQ + s; p[0] = f2bf(a); p[SEQ] = f2bf(b); p[2 * SEQ] = f2bf(c); p[3 * SEQ] = f2bf(d); }
.LBB0_584:
	s_andn2_saveexec_b64 s[6:7], s[6:7]
	s_cbranch_execz .LBB0_586
	v_lshrrev_b32_e32 v22, 14, v66
	v_and_b32_e32 v24, 0x1c0, v22
	v_lshlrev_b32_e32 v24, 14, v24
	v_bfe_u32 v23, v22, 4, 2
	v_lshl_or_b32 v24, v23, 11, v24
	v_and_b32_e32 v23, 15, v22
	v_lshl_or_b32 v24, v23, 6, v24
	v_lshrrev_b32_e32 v23, 6, v27
	v_lshl_or_b32 v24, v23, 13, v24
	v_bfe_u32 v23, v27, 5, 1
	v_lshl_or_b32 v24, v23, 10, v24
	v_and_b32_e32 v23, 31, v27
	v_lshl_or_b32 v24, v23, 1, v24
	v_mov_b32_e32 v25, v1
	v_lshl_add_u64 v[22:23], s[10:11], 0, v[24:25]
	v_cvt_pk_bf16_f32 v18, v18, s0
	flat_store_short v[22:23], v18
	v_add_co_u32_e32 v18, vcc, 0x40, v22
	v_cvt_pk_bf16_f32 v24, v19, s0
	s_nop 0
	v_addc_co_u32_e32 v19, vcc, 0, v23, vcc
	flat_store_short v[18:19], v24
	v_add_co_u32_e32 v18, vcc, 0x80, v22
	v_cvt_pk_bf16_f32 v20, v20, s0
	s_nop 0
	v_addc_co_u32_e32 v19, vcc, 0, v23, vcc
	flat_store_short v[18:19], v20
	v_add_co_u32_e32 v18, vcc, 0xc0, v22
	v_cvt_pk_bf16_f32 v20, v21, s0
	s_nop 0
	v_addc_co_u32_e32 v19, vcc, 0, v23, vcc
	flat_store_short v[18:19], v20

; DI bf16_t f2bf(float a) { return (bf16_t)(pk2(a, 0.f) & 0xffffu); }
;   DI void store(int m, int n, float a, float b, float c, float d) const {
;     int bb = m >> 13, s = m & (SEQ - 1);
;     if (n >= C_VS && n < C_KW) { int e = n - C_VS; bf16_t* p = vsT + ((size_t)(bb * 128 + e)) * SEQ + s; p[0] = f2bf(a); p[SEQ] = f2bf(b); p[2 * SEQ] = f2bf(c); p[3 * SEQ] = f2bf(d); }
.LBB0_599:
	s_andn2_saveexec_b64 s[18:19], s[18:19]
	s_cbranch_execz .LBB0_601
	v_lshrrev_b32_e32 v20, 14, v70
	v_and_b32_e32 v22, 0x1c0, v20
	v_lshlrev_b32_e32 v22, 14, v22
	v_bfe_u32 v21, v20, 4, 2
	v_lshl_or_b32 v22, v21, 11, v22
	v_and_b32_e32 v21, 15, v20
	v_lshl_or_b32 v22, v21, 6, v22
	v_lshrrev_b32_e32 v21, 6, v19
	v_lshl_or_b32 v22, v21, 13, v22
	v_bfe_u32 v21, v19, 5, 1
	v_lshl_or_b32 v22, v21, 10, v22
	v_and_b32_e32 v21, 31, v19
	v_lshl_or_b32 v22, v21, 1, v22
	v_mov_b32_e32 v23, v1
	v_lshl_add_u64 v[20:21], s[10:11], 0, v[22:23]
	v_cvt_pk_bf16_f32 v14, v14, s0
	flat_store_short v[20:21], v14
	v_add_co_u32_e32 v14, vcc, 0x40, v20
	v_cvt_pk_bf16_f32 v22, v15, s0
	s_nop 0
	v_addc_co_u32_e32 v15, vcc, 0, v21, vcc
	flat_store_short v[14:15], v22
	v_add_co_u32_e32 v14, vcc, 0x80, v20
	v_cvt_pk_bf16_f32 v16, v16, s0
	s_nop 0
	v_addc_co_u32_e32 v15, vcc, 0, v21, vcc
	flat_store_short v[14:15], v16
	v_add_co_u32_e32 v14, vcc, 0xc0, v20
	v_cvt_pk_bf16_f32 v16, v17, s0
	s_nop 0
	v_addc_co_u32_e32 v15, vcc, 0, v21, vcc
	flat_store_short v[14:15], v16

; DI bf16_t f2bf(float a) { return (bf16_t)(pk2(a, 0.f) & 0xffffu); }
;   DI void store(int m, int n, float a, float b, float c, float d) const {
;     int bb = m >> 13, s = m & (SEQ - 1);
;     if (n >= C_VS && n < C_KW) { int e = n - C_VS; bf16_t* p = vsT + ((size_t)(bb * 128 + e)) * SEQ + s; p[0] = f2bf(a); p[SEQ] = f2bf(b); p[2 * SEQ] = f2bf(c); p[3 * SEQ] = f2bf(d); }
.LBB0_607:
	s_andn2_saveexec_b64 s[6:7], s[6:7]
	s_cbranch_execz .LBB0_609
	v_lshrrev_b32_e32 v14, 14, v66
	v_and_b32_e32 v16, 0x1c0, v14
	v_lshlrev_b32_e32 v16, 14, v16
	v_bfe_u32 v15, v14, 4, 2
	v_lshl_or_b32 v16, v15, 11, v16
	v_and_b32_e32 v15, 15, v14
	v_lshl_or_b32 v16, v15, 6, v16
	v_lshrrev_b32_e32 v15, 6, v19
	v_lshl_or_b32 v16, v15, 13, v16
	v_bfe_u32 v15, v19, 5, 1
	v_lshl_or_b32 v16, v15, 10, v16
	v_and_b32_e32 v15, 31, v19
	v_lshl_or_b32 v16, v15, 1, v16
	v_mov_b32_e32 v17, v1
	v_lshl_add_u64 v[14:15], s[10:11], 0, v[16:17]
	v_cvt_pk_bf16_f32 v10, v10, s0
	flat_store_short v[14:15], v10
	v_add_co_u32_e32 v10, vcc, 0x40, v14
	v_cvt_pk_bf16_f32 v16, v11, s0
	s_nop 0
	v_addc_co_u32_e32 v11, vcc, 0, v15, vcc
	flat_store_short v[10:11], v16
	v_add_co_u32_e32 v10, vcc, 0x80, v14
	v_cvt_pk_bf16_f32 v12, v12, s0
	s_nop 0
	v_addc_co_u32_e32 v11, vcc, 0, v15, vcc
	flat_store_short v[10:11], v12
	v_add_co_u32_e32 v10, vcc, 0xc0, v14
	v_cvt_pk_bf16_f32 v12, v13, s0
	s_nop 0
	v_addc_co_u32_e32 v11, vcc, 0, v15, vcc
	flat_store_short v[10:11], v12

; DI bf16_t f2bf(float a) { return (bf16_t)(pk2(a, 0.f) & 0xffffu); }
;   DI void store(int m, int n, float a, float b, float c, float d) const {
;     int bb = m >> 13, s = m & (SEQ - 1);
;     if (n >= C_VS && n < C_KW) { int e = n - C_VS; bf16_t* p = vsT + ((size_t)(bb * 128 + e)) * SEQ + s; p[0] = f2bf(a); p[SEQ] = f2bf(b); p[2 * SEQ] = f2bf(c); p[3 * SEQ] = f2bf(d); }
.LBB0_622:
	s_andn2_saveexec_b64 s[16:17], s[16:17]
	s_cbranch_execz .LBB0_624
	v_lshrrev_b32_e32 v12, 14, v70
	v_and_b32_e32 v0, 0x1c0, v12
	v_lshlrev_b32_e32 v0, 14, v0
	v_bfe_u32 v13, v12, 4, 2
	v_lshl_or_b32 v0, v13, 11, v0
	v_and_b32_e32 v13, 15, v12
	v_lshl_or_b32 v0, v13, 6, v0
	v_lshrrev_b32_e32 v13, 6, v11
	v_lshl_or_b32 v0, v13, 13, v0
	v_bfe_u32 v13, v11, 5, 1
	v_lshl_or_b32 v0, v13, 10, v0
	v_and_b32_e32 v13, 31, v11
	v_lshl_or_b32 v0, v13, 1, v0
	v_lshl_add_u64 v[12:13], s[10:11], 0, v[0:1]
	v_cvt_pk_bf16_f32 v0, v2, s0
	v_add_co_u32_e32 v2, vcc, 0x40, v12
	flat_store_short v[12:13], v0
	v_cvt_pk_bf16_f32 v0, v3, s0
	v_addc_co_u32_e32 v3, vcc, 0, v13, vcc
	flat_store_short v[2:3], v0
	v_add_co_u32_e32 v2, vcc, 0x80, v12
	v_cvt_pk_bf16_f32 v0, v4, s0
	s_nop 0
	v_addc_co_u32_e32 v3, vcc, 0, v13, vcc
	flat_store_short v[2:3], v0
	v_add_co_u32_e32 v2, vcc, 0xc0, v12
	v_cvt_pk_bf16_f32 v0, v5, s0
	s_nop 0
	v_addc_co_u32_e32 v3, vcc, 0, v13, vcc
	flat_store_short v[2:3], v0

; DI bf16_t f2bf(float a) { return (bf16_t)(pk2(a, 0.f) & 0xffffu); }
;   DI void store(int m, int n, float a, float b, float c, float d) const {
;     int bb = m >> 13, s = m & (SEQ - 1);
;     if (n >= C_VS && n < C_KW) { int e = n - C_VS; bf16_t* p = vsT + ((size_t)(bb * 128 + e)) * SEQ + s; p[0] = f2bf(a); p[SEQ] = f2bf(b); p[2 * SEQ] = f2bf(c); p[3 * SEQ] = f2bf(d); }
;     else if (n >= C_VW && n < C_GATE) { int e = n - C_VW; bf16_t* p = vwT + ((size_t)(bb * 128 + e)) * SEQ + s; p[0] = f2bf(a); p[SEQ] = f2bf(b); p[2 * SEQ] = f2bf(c); p[3 * SEQ] = f2bf(d); }
.LBB0_630:
	s_andn2_saveexec_b64 s[4:5], s[4:5]
	s_cbranch_execz .LBB0_259
	v_lshrrev_b32_e32 v2, 14, v66
	v_and_b32_e32 v0, 0x1c0, v2
	v_lshlrev_b32_e32 v0, 14, v0
	v_bfe_u32 v3, v2, 4, 2
	v_lshl_or_b32 v0, v3, 11, v0
	v_and_b32_e32 v3, 15, v2
	v_lshl_or_b32 v0, v3, 6, v0
	v_lshrrev_b32_e32 v3, 6, v11
	v_lshl_or_b32 v0, v3, 13, v0
	v_bfe_u32 v3, v11, 5, 1
	v_lshl_or_b32 v0, v3, 10, v0
	v_and_b32_e32 v3, 31, v11
	v_lshl_or_b32 v0, v3, 1, v0
	v_lshl_add_u64 v[2:3], s[10:11], 0, v[0:1]
	v_cvt_pk_bf16_f32 v0, v6, s0
	v_add_co_u32_e32 v4, vcc, 0x40, v2
	flat_store_short v[2:3], v0
	v_cvt_pk_bf16_f32 v0, v7, s0
	v_addc_co_u32_e32 v5, vcc, 0, v3, vcc
	flat_store_short v[4:5], v0
	v_add_co_u32_e32 v4, vcc, 0x80, v2
	v_cvt_pk_bf16_f32 v0, v8, s0
	s_nop 0
	v_addc_co_u32_e32 v5, vcc, 0, v3, vcc
	v_add_co_u32_e32 v2, vcc, 0xc0, v2
	flat_store_short v[4:5], v0
	v_cvt_pk_bf16_f32 v0, v9, s0
	v_addc_co_u32_e32 v3, vcc, 0, v3, vcc
	flat_store_short v[2:3], v0
	s_branch .LBB0_259

; template <class T> DI T* opqp(T* p) { unsigned long long v = (unsigned long long)p; asm volatile("" : "+s"(v)); return (T*)v; }
; DI int tid_of(int wave_s) { unsigned z = 0; asm volatile("" : "+s"(z)); int l = __builtin_amdgcn_mbcnt_hi(~0u, __builtin_amdgcn_mbcnt_lo(~0u, z)); return wave_s * 64 + l; }
; DI int pi_row(int r) { return (r & 0x13) | ((r & 4) << 1) | ((r & 8) >> 1); }
; #define P kparams()
; DI void nsa_phase(unsigned char* lds, KParamPtr P, int wv) {
;   unsigned char* wsq = opqp(P->ws);
;   const float* tab = (const float*)(lds + LDS_TAB);
;   const int tid = tid_of(wv), lane = tid & 63, wave = tid >> 6, l31 = lane & 31, hh = lane >> 5;
;   unsigned char* selL = lds + LDS_WORK + wave * 512;
;   float* scw = (float*)(lds + LDS_WORK + 4096 + wave * 16384);
;   const bf16_t* proj = (const bf16_t*)(wsq + OFF_U + U_PROJ);
;   const bf16_t* vsT = (const bf16_t*)(wsq + OFF_U + U_VST);
;   const bf16_t* vwT = (const bf16_t*)(wsq + OFF_U + U_VWT);
;   const bf16_t* kc = (const bf16_t*)(wsq + OFF_MISC + MS_KC);
;   const bf16_t* vcT = (const bf16_t*)(wsq + OFF_MISC + MS_VCT);
;   float* part = (float*)(wsq + OFF_HB);
;   bf16_t* ao = (bf16_t*)(wsq + OFF_AO);
;   const int nw = gridDim.x * 8, gw = blockIdx.x * 8 + wave;
;   const int pr = pi_row(l31);
;   for (int it = gw; it < 2048; it += nw) {
;     const int blk_ = it >> 3, combo_ = blk_ & 7;
;     const int b = combo_ >> 1, g = combo_ & 1, tile = ((blk_ >> 3) << 3) + (it & 7), t0 = tile * 32, t = t0 + l31;
;     const size_t tok = (size_t)b * SEQ + t;
;     const bf16_t* kcb = kc + (size_t)((b * 2 + g) * 512) * 64;
;     const bf16_t* vcb = vcT + (size_t)((b * 2 + g) * 64) * 512;
; #pragma unroll 1
;     for (int x = 0; x < 64; ++x) scw[x * 64 + lane] = 0.f;
;     const int nkt = (2 * tile + 1 + 31) >> 5;
; #pragma unroll 1
;     ...
;       const int col = lane & 15, q4 = lane >> 4;
;       const int qq = col >> 2, hcol = g * 4 + (col & 3);
;       const float* tabc = tab + hcol * 128;
;       const int rk = 8 * (col >> 2) + (col & 3);
;       const unsigned kbase = (unsigned)((b * SEQ + rk) * EIN + C_KS + g * 64 + q4 * 8);
;       const unsigned vbase = (unsigned)(((b * 2 + g) * 64 + col) * SEQ + q4 * 8);
.LBB0_933:
	s_or_b64 exec, exec, s[4:5]
	s_mov_b64 s[4:5], s[64:65]
	s_barrier
	s_load_dwordx2 s[6:7], s[4:5], 0xc8
	s_mov_b32 s2, s89
	s_waitcnt lgkmcnt(0)
	v_readlane_b32 s4, v254, 0
	v_mbcnt_lo_u32_b32 v0, -1, s2
	v_mbcnt_hi_u32_b32 v4, -1, v0
	v_add_u32_e32 v3, s4, v4
	v_ashrrev_i32_e32 v2, 6, v3
	v_readlane_b32 s2, v254, 33
	v_readlane_b32 s5, v254, 1
	s_nop 0
	v_add_u32_e32 v165, s2, v2
	s_movk_i32 s2, 0x800
	v_cmp_gt_i32_e32 vcc, s2, v165
	s_and_saveexec_b64 s[18:19], vcc
	s_cbranch_execz .LBB0_1158
	v_lshlrev_b32_e32 v6, 1, v4
	v_lshrrev_b32_e32 v8, 1, v4
	v_lshl_add_u32 v164, v2, 9, 0
	v_and_b32_e32 v0, 19, v4
	v_and_b32_e32 v6, 8, v6
	v_and_b32_e32 v7, 4, v8
	s_movk_i32 s2, 0x3e00
	v_and_b32_e32 v5, 63, v4
	s_add_u32 s20, s6, 0x8000000
	v_or3_b32 v224, v7, v0, v6
	v_mad_u64_u32 v[6:7], s[4:5], v2, s2, v[164:165]
	v_and_b32_e32 v222, 31, v4
	v_bfe_u32 v223, v4, 5, 1
	s_addc_u32 s21, s7, 0
	v_lshlrev_b32_e32 v7, 2, v5
	v_cmp_gt_u32_e64 s[4:5], 32, v5
	v_and_b32_e32 v11, 15, v4
	v_bfe_u32 v229, v4, 2, 2
	v_and_b32_e32 v230, 3, v4
	v_and_b32_e32 v170, 24, v8
	v_mov_b32_e32 v171, v1
	v_and_b32_e32 v4, 48, v4
	v_mov_b32_e32 v5, v1
	v_lshlrev_b32_e32 v0, 4, v223
	v_lshl_add_u64 v[172:173], s[20:21], 0, v[4:5]
	v_lshl_add_u64 v[174:175], s[6:7], 0, v[4:5]
	v_lshl_add_u64 v[4:5], s[6:7], 0, v[170:171]
	s_mov_b64 s[8:9], 0x4000000
	v_lshl_add_u64 v[176:177], v[4:5], 0, s[8:9]
	v_lshl_or_b32 v4, v224, 7, v0
	v_mov_b32_e32 v5, v1
	s_add_u32 s22, s6, 0x11e00000
	v_lshl_add_u64 v[166:167], s[20:21], 0, v[0:1]
	v_lshlrev_b32_e32 v10, 2, v222
	v_lshl_add_u64 v[168:169], s[6:7], 0, v[0:1]
	v_lshl_add_u64 v[4:5], s[6:7], 0, v[4:5]
	s_mov_b64 s[8:9], 0x1a600000
	v_lshl_or_b32 v0, v222, 10, v0
	s_addc_u32 s23, s7, 0
	v_add_u32_e32 v225, v6, v7
	v_add_u32_e32 v226, v6, v10
	v_lshlrev_b32_e32 v6, 8, v223
	v_bfe_u32 v171, v3, 6, 3
	v_lshl_add_u64 v[178:179], v[4:5], 0, s[8:9]
	v_lshlrev_b32_e32 v3, 7, v223
	v_lshl_add_u64 v[4:5], s[6:7], 0, v[0:1]
	v_lshlrev_b32_e32 v0, 14, v2
	v_lshlrev_b32_e32 v9, 3, v223
	v_xor_b32_e32 v227, 0x80, v7
	v_lshlrev_b32_e32 v7, 4, v222
	v_sub_u32_e32 v234, v222, v3
	v_lshlrev_b32_e32 v3, 10, v171
	s_mov_b64 s[8:9], 0x1a708020
	v_or3_b32 v0, v0, v6, v10
	v_readlane_b32 s2, v255, 9
	s_add_u32 s24, s6, 0x12680020
	v_lshlrev_b32_e32 v228, 1, v223
	v_or_b32_e32 v232, 0x400, v9
	v_or_b32_e32 v233, 0x300, v170
	v_add_u32_e32 v235, 0xfffffdf1, v3
	v_lshl_add_u64 v[180:181], v[4:5], 0, s[8:9]
	v_add_u32_e32 v236, s2, v0
	v_or_b32_e32 v237, 31, v3
	v_sub_u32_e32 v238, v222, v9
	s_addc_u32 s25, s7, 0
	v_lshl_or_b32 v239, v222, 13, v9
	s_mov_b64 s[26:27], 0
	v_add_u32_e32 v240, v164, v7
	v_lshlrev_b32_e32 v241, 5, v11
	s_branch .LBB0_936

; DI void nsa_phase(unsigned char* lds, KParamPtr P, int wv) {
;     ...
;         auto load_k = [&](int jb) {
;           const unsigned ko = kbase + (unsigned)(jb * 64 * EIN);
; #pragma unroll
;           for (int hf = 0; hf < 2; ++hf)
; #pragma unroll
;             for (int tl = 0; tl < 2; ++tl) {
;               kf[(hf * 2 + tl) * 2 + 0] = ldg8(proj + ko + (unsigned)((hf * 32 + 4 * tl) * EIN));
;               kf[(hf * 2 + tl) * 2 + 1] = ldg8(proj + ko + (unsigned)((hf * 32 + 4 * tl) * EIN + 32));
;             }
;         };
;         auto load_v = [&](int jb) {
;           const unsigned vo = vbase + (unsigned)(jb * 64);
; #pragma unroll
;           for (int hf = 0; hf < 2; ++hf)
; #pragma unroll
;             for (int e = 0; e < 4; ++e) vf[hf * 4 + e] = ldg8(vsT + vo + (unsigned)(e * 16 * SEQ + hf * 32));
;         };
;         int jb = next_blk();
;         if (jb >= 0) { load_k(jb); load_v(jb); }
.LBB0_1092:
	v_mad_i32_i24 v0, v136, s0, v123
	v_lshl_add_u64 v[14:15], v[0:1], 1, s[20:21]
	v_add_co_u32_e32 v16, vcc, 0x4000, v14
	flat_load_dwordx4 v[50:53], v[14:15]
	flat_load_dwordx4 v[54:57], v[14:15] offset:64
	v_addc_co_u32_e32 v17, vcc, 0, v15, vcc
	flat_load_dwordx4 v[58:61], v[16:17] offset:3840
	flat_load_dwordx4 v[62:65], v[16:17] offset:3904
	v_add_co_u32_e32 v16, vcc, 0x27000, v14
	v_lshlrev_b32_e32 v0, 12, v136
	s_nop 0
	v_addc_co_u32_e32 v17, vcc, 0, v15, vcc
	v_add_co_u32_e32 v14, vcc, 0x2c000, v14
	v_add_lshl_u32 v0, v0, v124, 1
	s_nop 0
	v_addc_co_u32_e32 v15, vcc, 0, v15, vcc
	flat_load_dwordx4 v[66:69], v[16:17] offset:2048
	flat_load_dwordx4 v[70:73], v[16:17] offset:2112
	flat_load_dwordx4 v[74:77], v[14:15] offset:1792
	flat_load_dwordx4 v[78:81], v[14:15] offset:1856
	v_lshl_add_u64 v[14:15], s[22:23], 0, v[0:1]
	v_add_co_u32_e32 v16, vcc, 0x800, v14
	s_nop 1
	v_addc_co_u32_e32 v17, vcc, 0, v15, vcc
	v_add_co_u32_e32 v18, vcc, 0x1000, v14
	s_nop 1
	v_addc_co_u32_e32 v19, vcc, 0, v15, vcc
	v_add_co_u32_e32 v20, vcc, 0x1800, v14
	s_nop 1
	v_addc_co_u32_e32 v21, vcc, 0, v15, vcc
	flat_load_dwordx4 v[82:85], v[14:15]
	flat_load_dwordx4 v[86:89], v[14:15] offset:1024
	flat_load_dwordx4 v[94:97], v[16:17]
	flat_load_dwordx4 v[90:93], v[16:17] offset:1024
	flat_load_dwordx4 v[102:105], v[18:19]
	flat_load_dwordx4 v[98:101], v[18:19] offset:1024
	flat_load_dwordx4 v[110:113], v[20:21]
	flat_load_dwordx4 v[106:109], v[20:21] offset:1024

; #define MFMA16(a, b, c) __builtin_amdgcn_mfma_f32_16x16x32_bf16((a), (b), (c), 0, 0, 0)
; DI unsigned pk2(float a, float b) { f32x2 v = {a, b}; bfx2 r = __builtin_convertvector(v, bfx2); return __builtin_bit_cast(unsigned, r); }
; DI float ex2(float x) { return __builtin_amdgcn_exp2f(x); }
; DI float red_max32(float x) { auto r = __builtin_amdgcn_permlane32_swap(__float_as_uint(x), __float_as_uint(x), false, false); return fmaxf(__uint_as_float(r[0]), __uint_as_float(r[1])); }
; DI float red_max16(float x) { auto r = __builtin_amdgcn_permlane16_swap(__float_as_uint(x), __float_as_uint(x), false, false); return fmaxf(__uint_as_float(r[0]), __uint_as_float(r[1])); }
; DI void nsa_phase(unsigned char* lds, KParamPtr P, int wv) {
;     ...
;           mloc = red_max16(mloc);
;           mloc = red_max32(mloc);
;           const float mn = fmaxf(m, mloc);
;           const float alpha = ex2(m - mn);
;           float ls = 0.f;
; #pragma unroll
;           for (int hf = 0; hf < 2; ++hf)
; #pragma unroll
;             for (int tl = 0; tl < 2; ++tl)
; #pragma unroll
;               for (int j = 0; j < 4; ++j) { float p = (a[hf][tl][j] > -1e29f) ? ex2(a[hf][tl][j] - mn) : 0.f; a[hf][tl][j] = p; ls += p; }
;           l = l * alpha + ls; m = mn;
; #pragma unroll
;           for (int e = 0; e < 4; ++e) O[e] *= alpha;
; #pragma unroll
;           for (int hf = 0; hf < 2; ++hf) {
;             u32x4 u; u.x = pk2(a[hf][0][0], a[hf][0][1]); u.y = pk2(a[hf][0][2], a[hf][0][3]); u.z = pk2(a[hf][1][0], a[hf][1][1]); u.w = pk2(a[hf][1][2], a[hf][1][3]);
;             const bf16x8 pf = __builtin_bit_cast(bf16x8, u);
; #pragma unroll
;             for (int e = 0; e < 4; ++e) O[e] = MFMA16(vf[hf * 4 + e], pf, O[e]);
;           }
;           if (jn >= 0) load_v(jn);
;           jb = jn;
.LBB0_1146:
	s_or_b64 exec, exec, s[16:17]
	v_mov_b32_e32 v30, v151
	s_nop 1
	v_permlane16_swap_b32_e32 v151, v30
	v_max_f32_e32 v30, v30, v30
	v_max_f32_e32 v31, v151, v151
	v_max_f32_e32 v30, v31, v30
	v_mov_b32_e32 v31, v30
	s_nop 1
	v_permlane32_swap_b32_e32 v30, v31
	v_max3_f32 v31, v135, v30, v31
	v_sub_f32_e32 v32, v137, v31
	v_exp_f32_e32 v32, v32
	v_cmp_lt_f32_e32 vcc, s62, v137
	v_sub_f32_e32 v30, v135, v31
	v_exp_f32_e32 v30, v30
	v_cndmask_b32_e32 v32, 0, v32, vcc
	v_cmp_lt_f32_e32 vcc, s62, v0
	v_sub_f32_e32 v0, v0, v31
	v_exp_f32_e32 v0, v0
	v_pk_mul_f32 v[28:29], v[28:29], v[30:31] op_sel_hi:[1,0]
	v_pk_mul_f32 v[26:27], v[26:27], v[30:31] op_sel_hi:[1,0]
	v_pk_mul_f32 v[24:25], v[24:25], v[30:31] op_sel_hi:[1,0]
	v_cndmask_b32_e32 v33, 0, v0, vcc
	v_sub_f32_e32 v0, v138, v31
	v_exp_f32_e32 v0, v0
	v_cmp_lt_f32_e32 vcc, s62, v138
	v_pk_mul_f32 v[22:23], v[22:23], v[30:31] op_sel_hi:[1,0]
	v_pk_mul_f32 v[20:21], v[20:21], v[30:31] op_sel_hi:[1,0]
	v_cndmask_b32_e32 v34, 0, v0, vcc
	v_sub_f32_e32 v0, v136, v31
	v_exp_f32_e32 v0, v0
	v_cmp_lt_f32_e32 vcc, s62, v136
	v_pk_mul_f32 v[18:19], v[18:19], v[30:31] op_sel_hi:[1,0]
	v_pk_mul_f32 v[16:17], v[16:17], v[30:31] op_sel_hi:[1,0]
	v_cndmask_b32_e32 v35, 0, v0, vcc
	v_sub_f32_e32 v0, v141, v31
	v_exp_f32_e32 v0, v0
	v_cmp_lt_f32_e32 vcc, s62, v141
	v_pk_mul_f32 v[14:15], v[14:15], v[30:31] op_sel_hi:[1,0]
	v_cvt_pk_bf16_f32 v138, v32, v33
	v_cndmask_b32_e32 v36, 0, v0, vcc
	v_sub_f32_e32 v0, v139, v31
	v_exp_f32_e32 v0, v0
	v_cmp_lt_f32_e32 vcc, s62, v139
	v_cvt_pk_bf16_f32 v139, v34, v35
	s_nop 0
	v_cndmask_b32_e32 v37, 0, v0, vcc
	v_sub_f32_e32 v0, v142, v31
	v_exp_f32_e32 v0, v0
	v_cmp_lt_f32_e32 vcc, s62, v142
	s_nop 1
	v_cndmask_b32_e32 v38, 0, v0, vcc
	v_sub_f32_e32 v0, v140, v31
	v_exp_f32_e32 v0, v0
	v_cmp_lt_f32_e32 vcc, s62, v140
	v_cvt_pk_bf16_f32 v140, v36, v37
	s_nop 0
	v_cndmask_b32_e32 v39, 0, v0, vcc
	v_sub_f32_e32 v0, v145, v31
	v_exp_f32_e32 v0, v0
	v_cmp_lt_f32_e32 vcc, s62, v145
	v_cvt_pk_bf16_f32 v141, v38, v39
	s_nop 0
	v_cndmask_b32_e32 v40, 0, v0, vcc
	v_sub_f32_e32 v0, v143, v31
	v_exp_f32_e32 v0, v0
	v_cmp_lt_f32_e32 vcc, s62, v143
	v_mfma_f32_16x16x32_bf16 v[26:29], v[82:85], v[138:141], v[26:29]
	s_nop 0
	v_cndmask_b32_e32 v41, 0, v0, vcc
	v_sub_f32_e32 v0, v146, v31
	v_exp_f32_e32 v0, v0
	v_cmp_lt_f32_e32 vcc, s62, v146
	v_mfma_f32_16x16x32_bf16 v[22:25], v[94:97], v[138:141], v[22:25]
	s_nop 0
	v_cndmask_b32_e32 v42, 0, v0, vcc
	v_sub_f32_e32 v0, v144, v31
	v_exp_f32_e32 v0, v0
	v_cmp_lt_f32_e32 vcc, s62, v144
	v_mfma_f32_16x16x32_bf16 v[18:21], v[102:105], v[138:141], v[18:21]
	s_nop 0
	v_cndmask_b32_e32 v43, 0, v0, vcc
	v_sub_f32_e32 v0, v148, v31
	v_exp_f32_e32 v0, v0
	v_cmp_lt_f32_e32 vcc, s62, v148
	v_mfma_f32_16x16x32_bf16 v[14:17], v[110:113], v[138:141], v[14:17]
	v_cvt_pk_bf16_f32 v138, v40, v41
	v_cndmask_b32_e32 v44, 0, v0, vcc
	v_sub_f32_e32 v0, v147, v31
	v_exp_f32_e32 v0, v0
	v_cmp_lt_f32_e32 vcc, s62, v147
	v_cvt_pk_bf16_f32 v139, v42, v43
	s_nop 0
	v_cndmask_b32_e32 v45, 0, v0, vcc
	v_sub_f32_e32 v0, v150, v31
	v_exp_f32_e32 v0, v0
	v_cmp_lt_f32_e32 vcc, s62, v150
	v_cvt_pk_bf16_f32 v140, v44, v45
	s_nop 0
	v_cndmask_b32_e32 v135, 0, v0, vcc
	v_sub_f32_e32 v0, v149, v31
	v_exp_f32_e32 v0, v0
	v_cmp_lt_f32_e32 vcc, s62, v149
	s_nop 1
	v_cndmask_b32_e32 v136, 0, v0, vcc
	v_cvt_pk_bf16_f32 v141, v135, v136
	s_nop 1
	v_mfma_f32_16x16x32_bf16 v[26:29], v[86:89], v[138:141], v[26:29]
	v_mfma_f32_16x16x32_bf16 v[22:25], v[90:93], v[138:141], v[22:25]
	v_mfma_f32_16x16x32_bf16 v[18:21], v[98:101], v[138:141], v[18:21]
	v_mfma_f32_16x16x32_bf16 v[14:17], v[106:109], v[138:141], v[14:17]
	s_and_saveexec_b64 s[16:17], s[14:15]
	s_cbranch_execz .LBB0_1095
	v_lshlrev_b32_e32 v0, 12, v134
	v_add_lshl_u32 v0, v0, v124, 1
	v_lshl_add_u64 v[86:87], s[22:23], 0, v[0:1]
	v_add_co_u32_e32 v90, vcc, 0x800, v86
	s_nop 1
	v_addc_co_u32_e32 v91, vcc, 0, v87, vcc
	v_add_co_u32_e32 v98, vcc, 0x1000, v86
	s_nop 1
	v_addc_co_u32_e32 v99, vcc, 0, v87, vcc
	v_add_co_u32_e32 v106, vcc, 0x1800, v86
	s_nop 1
	v_addc_co_u32_e32 v107, vcc, 0, v87, vcc
	flat_load_dwordx4 v[82:85], v[86:87]
	s_nop 0
	flat_load_dwordx4 v[86:89], v[86:87] offset:1024
	s_nop 0
	flat_load_dwordx4 v[94:97], v[90:91]
	s_nop 0
	flat_load_dwordx4 v[90:93], v[90:91] offset:1024
	s_nop 0
	flat_load_dwordx4 v[102:105], v[98:99]
	s_nop 0
	flat_load_dwordx4 v[98:101], v[98:99] offset:1024
	s_nop 0
	flat_load_dwordx4 v[110:113], v[106:107]
	s_nop 0
	flat_load_dwordx4 v[106:109], v[106:107] offset:1024
	s_branch .LBB0_1095
